# sample K/V cache conversion moved out of the FFN-down phase: half after gate/in projection (128 idle workgroups), half after FFN-up (160 idle workgroups); split-K finisher keeps 24 partial loads in fl
# baseline (speedup 1.0000x reference)
.LBB0_739:
	v_readlane_b32 s0, v255, 16
	v_readlane_b32 s1, v255, 17
	s_andn2_b64 vcc, exec, s[0:1]
	s_cbranch_vccnz .Lpc1_done
	s_sub_i32 s2, s92, 0x80
	s_cmp_lt_i32 s2, 0
	s_cbranch_scc1 .Lpc1_done
	s_movk_i32 s14, 0x80
	s_mov_b64 s[98:99], s[8:9]
	v_readlane_b32 s8, v255, 2
	v_readlane_b32 s9, v255, 3
	v_mbcnt_lo_u32_b32 v0, -1, 0
	v_mbcnt_hi_u32_b32 v0, -1, v0
	v_readlane_b32 s0, v255, 4
	s_lshl_b32 s10, s2, 5
	s_nop 0
	v_or_b32_e32 v0, s0, v0
	s_nop 0
	v_readfirstlane_b32 s0, v0
	s_ashr_i32 s0, s0, 4
	s_and_b32 s11, s0, -4
	s_add_i32 s0, s11, s10
	s_cmp_gt_i32 s0, 0x7fff
	v_mbcnt_lo_u32_b32 v0, -1, 0
	v_mbcnt_hi_u32_b32 v0, -1, v0
	s_cbranch_scc1 .Lpc1_restore
	s_load_dwordx2 s[2:3], s[8:9], 0x108
	s_load_dwordx4 s[4:7], s[8:9], 0x30
	v_readlane_b32 s8, v255, 14
	v_lshlrev_b32_e32 v0, 3, v0
	v_and_b32_e32 v12, 0x1f8, v0
	s_waitcnt lgkmcnt(0)
	s_add_u32 s0, s2, 0x50c00000
	s_addc_u32 s1, s3, 0
	s_add_u32 s2, s2, 0x55400000
	s_addc_u32 s3, s3, 0
	s_add_i32 s8, s8, s10
	s_lshl_b32 s15, s54, 16
	s_lshl_b32 s14, s14, 5
	s_add_i32 s20, s8, s11
	s_add_i32 s15, s15, 0x8000
	s_ashr_i32 s21, s20, 31
	s_ashr_i32 s22, s14, 31

.Lpc1_restore:
	s_mov_b64 s[8:9], s[98:99]
.Lpc1_done:
	v_readlane_b32 s6, v255, 6
	v_readlane_b32 s7, v255, 7
	v_readlane_b32 s0, v255, 8
	s_waitcnt vmcnt(0)
	s_waitcnt vmcnt(0) lgkmcnt(0)
	s_barrier
	s_mov_b64 s[4:5], exec
	v_readlane_b32 s2, v255, 9
	v_readlane_b32 s3, v255, 10
	s_and_b64 s[2:3], s[4:5], s[2:3]
	s_mov_b64 exec, s[2:3]
	s_cbranch_execz .LBB0_791
	v_readlane_b32 s1, v255, 12
	s_waitcnt vmcnt(0) expcnt(0) lgkmcnt(0)
	s_nop 0
	v_mov_b32_e32 v0, s1
	ds_read_b32 v2, v0
	v_readlane_b32 s1, v255, 13
	s_waitcnt lgkmcnt(0)
	v_cmp_ne_u32_e32 vcc, 0, v2
	v_mov_b32_e32 v0, s1
	ds_read_b32 v0, v0
	s_cbranch_vccnz .LBB0_755
	v_readlane_b32 s8, v255, 0
	v_readlane_b32 s9, v255, 1
	s_load_dwordx2 s[2:3], s[8:9], 0x4
	s_add_u32 s8, s6, 0x1000
	s_addc_u32 s9, s7, 0
	s_add_u32 s10, s6, 0x1100
	s_addc_u32 s11, s7, 0
	s_add_u32 s16, s6, 0x1200
	s_addc_u32 s17, s7, 0
	s_waitcnt lgkmcnt(0)
	s_mul_i32 s1, s2, s93
	s_add_u32 s18, s6, 0x1300
	s_mul_i32 s1, s1, s3
	s_addc_u32 s19, s7, 0
	s_mov_b32 s2, 1
	s_branch .LBB0_743

.LBB0_1197:
	v_readlane_b32 s0, v255, 16
	v_readlane_b32 s1, v255, 17
	s_andn2_b64 vcc, exec, s[0:1]
	s_cbranch_vccnz .Lpc2_done
	s_sub_i32 s2, s92, 0x60
	s_cmp_lt_i32 s2, 0
	s_cbranch_scc1 .Lpc2_done
	s_movk_i32 s14, 0xa0
	s_mov_b64 s[98:99], s[8:9]
	v_readlane_b32 s8, v255, 2
	v_readlane_b32 s9, v255, 3
	v_mbcnt_lo_u32_b32 v0, -1, 0
	v_mbcnt_hi_u32_b32 v0, -1, v0
	v_readlane_b32 s0, v255, 4
	s_lshl_b32 s10, s2, 5
	s_nop 0
	v_or_b32_e32 v0, s0, v0
	s_nop 0
	v_readfirstlane_b32 s0, v0
	s_ashr_i32 s0, s0, 4
	s_and_b32 s11, s0, -4
	s_add_i32 s0, s11, s10
	s_cmp_gt_i32 s0, 0x7fff
	v_mbcnt_lo_u32_b32 v0, -1, 0
	v_mbcnt_hi_u32_b32 v0, -1, v0
	s_cbranch_scc1 .Lpc2_restore
	s_load_dwordx2 s[2:3], s[8:9], 0x108
	s_load_dwordx4 s[4:7], s[8:9], 0x30
	v_readlane_b32 s8, v255, 14
	v_lshlrev_b32_e32 v0, 3, v0
	v_and_b32_e32 v12, 0x1f8, v0
	s_waitcnt lgkmcnt(0)
	s_add_u32 s0, s2, 0x50c00000
	s_addc_u32 s1, s3, 0
	s_add_u32 s2, s2, 0x55400000
	s_addc_u32 s3, s3, 0
	s_add_i32 s8, s8, s10
	s_add_i32 s8, s8, 0x8000
	s_lshl_b32 s15, s54, 16
	s_lshl_b32 s14, s14, 5
	s_add_i32 s20, s8, s11
	s_add_i32 s15, s15, 0x10000
	s_ashr_i32 s21, s20, 31
	s_ashr_i32 s22, s14, 31
